# pool phase: read-once silu-gate row loads marked nt (z rows, which are re-read as the window's leaving rows, keep the default policy)
# baseline (speedup 1.0000x reference)
.Lpool_lb_done:
	s_add_u32 s98, s8, 0x0
	s_addc_u32 s99, s9, 0
	global_load_dwordx4 v[4:7], v2, s[98:99]
	s_add_u32 s98, s10, 0x0
	s_addc_u32 s99, s11, 0
	global_load_dwordx4 v[36:39], v2, s[98:99] nt
	s_add_u32 s98, s40, 0x0
	s_addc_u32 s99, s41, 0
	global_load_dwordx4 v[68:71], v2, s[98:99]
	s_add_u32 s98, s8, 0x1000
	s_addc_u32 s99, s9, 0
	global_load_dwordx4 v[8:11], v2, s[98:99]
	s_add_u32 s98, s10, 0x1000
	s_addc_u32 s99, s11, 0
	global_load_dwordx4 v[40:43], v2, s[98:99] nt
	s_add_u32 s98, s40, 0x1000
	s_addc_u32 s99, s41, 0
	global_load_dwordx4 v[72:75], v2, s[98:99]
	s_add_u32 s98, s8, 0x2000
	s_addc_u32 s99, s9, 0
	global_load_dwordx4 v[12:15], v2, s[98:99]
	s_add_u32 s98, s10, 0x2000
	s_addc_u32 s99, s11, 0
	global_load_dwordx4 v[44:47], v2, s[98:99] nt
	s_add_u32 s98, s40, 0x2000
	s_addc_u32 s99, s41, 0
	global_load_dwordx4 v[76:79], v2, s[98:99]
	s_add_u32 s98, s8, 0x3000
	s_addc_u32 s99, s9, 0
	global_load_dwordx4 v[16:19], v2, s[98:99]
	s_add_u32 s98, s10, 0x3000
	s_addc_u32 s99, s11, 0
	global_load_dwordx4 v[48:51], v2, s[98:99] nt
	s_add_u32 s98, s40, 0x3000
	s_addc_u32 s99, s41, 0
	global_load_dwordx4 v[80:83], v2, s[98:99]
	s_add_u32 s98, s8, 0x4000
	s_addc_u32 s99, s9, 0
	global_load_dwordx4 v[20:23], v2, s[98:99]
	s_add_u32 s98, s10, 0x4000
	s_addc_u32 s99, s11, 0
	global_load_dwordx4 v[52:55], v2, s[98:99] nt
	s_add_u32 s98, s40, 0x4000
	s_addc_u32 s99, s41, 0
	global_load_dwordx4 v[84:87], v2, s[98:99]
	s_add_u32 s98, s8, 0x5000
	s_addc_u32 s99, s9, 0
	global_load_dwordx4 v[24:27], v2, s[98:99]
	s_add_u32 s98, s10, 0x5000
	s_addc_u32 s99, s11, 0
	global_load_dwordx4 v[56:59], v2, s[98:99] nt
	s_add_u32 s98, s40, 0x5000
	s_addc_u32 s99, s41, 0
	global_load_dwordx4 v[88:91], v2, s[98:99]
	s_add_u32 s98, s8, 0x6000
	s_addc_u32 s99, s9, 0
	global_load_dwordx4 v[28:31], v2, s[98:99]
	s_add_u32 s98, s10, 0x6000
	s_addc_u32 s99, s11, 0
	global_load_dwordx4 v[60:63], v2, s[98:99] nt
	s_add_u32 s98, s40, 0x6000
	s_addc_u32 s99, s41, 0
	global_load_dwordx4 v[92:95], v2, s[98:99]
	s_add_u32 s98, s8, 0x7000
	s_addc_u32 s99, s9, 0
	global_load_dwordx4 v[32:35], v2, s[98:99]
	s_add_u32 s98, s10, 0x7000
	s_addc_u32 s99, s11, 0
	global_load_dwordx4 v[64:67], v2, s[98:99] nt
	s_add_u32 s98, s40, 0x7000
	s_addc_u32 s99, s41, 0
	global_load_dwordx4 v[96:99], v2, s[98:99]
	s_waitcnt vmcnt(0)
	s_mov_b32 s39, 3

.Lpool_fa_0:
	v_lshlrev_b32_e32 v116, 16, v4
	v_and_b32_e32 v117, 0xffff0000, v4
	v_lshlrev_b32_e32 v118, 16, v5
	v_and_b32_e32 v119, 0xffff0000, v5
	v_lshlrev_b32_e32 v120, 16, v6
	v_and_b32_e32 v121, 0xffff0000, v6
	v_lshlrev_b32_e32 v122, 16, v7
	v_and_b32_e32 v123, 0xffff0000, v7
	v_pk_add_f32 v[100:101], v[100:101], v[116:117]
	v_pk_add_f32 v[102:103], v[102:103], v[118:119]
	v_pk_add_f32 v[104:105], v[104:105], v[120:121]
	v_pk_add_f32 v[106:107], v[106:107], v[122:123]
	v_fma_f32 v116, v154, v100, -v116
	v_fma_f32 v117, v154, v101, -v117
	v_fma_f32 v118, v154, v102, -v118
	v_fma_f32 v119, v154, v103, -v119
	v_fma_f32 v120, v154, v104, -v120
	v_fma_f32 v121, v154, v105, -v121
	v_fma_f32 v122, v154, v106, -v122
	v_fma_f32 v123, v154, v107, -v123
	v_mul_f32_e32 v116, v108, v116
	v_mul_f32_e32 v117, v109, v117
	v_mul_f32_e32 v118, v110, v118
	v_mul_f32_e32 v119, v111, v119
	v_mul_f32_e32 v120, v112, v120
	v_mul_f32_e32 v121, v113, v121
	v_mul_f32_e32 v122, v114, v122
	v_mul_f32_e32 v123, v115, v123
	v_lshlrev_b32_e32 v128, 16, v36
	v_and_b32_e32 v129, 0xffff0000, v36
	v_mul_f32_e32 v116, v116, v128
	v_mul_f32_e32 v117, v117, v129
	v_cvt_pk_bf16_f32 v124, v116, v117
	v_lshlrev_b32_e32 v128, 16, v37
	v_and_b32_e32 v129, 0xffff0000, v37
	v_mul_f32_e32 v118, v118, v128
	v_mul_f32_e32 v119, v119, v129
	v_cvt_pk_bf16_f32 v125, v118, v119
	v_lshlrev_b32_e32 v128, 16, v38
	v_and_b32_e32 v129, 0xffff0000, v38
	v_mul_f32_e32 v120, v120, v128
	v_mul_f32_e32 v121, v121, v129
	v_cvt_pk_bf16_f32 v126, v120, v121
	v_lshlrev_b32_e32 v128, 16, v39
	v_and_b32_e32 v129, 0xffff0000, v39
	v_mul_f32_e32 v122, v122, v128
	v_mul_f32_e32 v123, v123, v129
	v_cvt_pk_bf16_f32 v127, v122, v123
	s_add_u32 s98, s12, 0
	s_addc_u32 s99, s13, 0
	global_store_dwordx4 v2, v[124:127], s[98:99]
	v_lshlrev_b32_e32 v116, 16, v68
	v_and_b32_e32 v117, 0xffff0000, v68
	v_lshlrev_b32_e32 v118, 16, v69
	v_and_b32_e32 v119, 0xffff0000, v69
	v_lshlrev_b32_e32 v120, 16, v70
	v_and_b32_e32 v121, 0xffff0000, v70
	v_lshlrev_b32_e32 v122, 16, v71
	v_and_b32_e32 v123, 0xffff0000, v71
	v_pk_add_f32 v[100:101], v[100:101], v[116:117] neg_lo:[0,1] neg_hi:[0,1]
	v_pk_add_f32 v[102:103], v[102:103], v[118:119] neg_lo:[0,1] neg_hi:[0,1]
	v_pk_add_f32 v[104:105], v[104:105], v[120:121] neg_lo:[0,1] neg_hi:[0,1]
	v_pk_add_f32 v[106:107], v[106:107], v[122:123] neg_lo:[0,1] neg_hi:[0,1]
	s_add_u32 s98, s8, 0x8000
	s_addc_u32 s99, s9, 0
	global_load_dwordx4 v[4:7], v2, s[98:99]
	s_add_u32 s98, s10, 0x8000
	s_addc_u32 s99, s11, 0
	global_load_dwordx4 v[36:39], v2, s[98:99] nt
	s_add_u32 s98, s40, 0x8000
	s_addc_u32 s99, s41, 0
	global_load_dwordx4 v[68:71], v2, s[98:99]
	s_add_u32 s100, s100, 1
	s_waitcnt vmcnt(28)
	v_mov_b32_e32 v154, s38
	s_cmp_lt_u32 s100, s30
	s_cbranch_scc0 .Lpool_fa_1
	v_mov_b32_e32 v72, 0
	v_mov_b32_e32 v73, 0
	v_mov_b32_e32 v74, 0
	v_mov_b32_e32 v75, 0
	s_add_u32 s98, s100, 1
	v_cvt_f32_u32_e32 v116, s98
	v_div_scale_f32 v117, s[98:99], v116, v116, 1.0
	v_rcp_f32_e32 v118, v117
	s_nop 1
	v_fma_f32 v119, -v117, v118, 1.0
	v_fmac_f32_e32 v118, v119, v118
	v_div_scale_f32 v119, vcc, 1.0, v116, 1.0
	v_mul_f32_e32 v120, v119, v118
	v_fma_f32 v121, -v117, v120, v119
	v_fmac_f32_e32 v120, v121, v118
	v_fma_f32 v117, -v117, v120, v119
	s_nop 1
	v_div_fmas_f32 v117, v117, v118, v120
	v_div_fixup_f32 v154, v117, v116, 1.0
.Lpool_fa_1:
	v_lshlrev_b32_e32 v116, 16, v8
	v_and_b32_e32 v117, 0xffff0000, v8
	v_lshlrev_b32_e32 v118, 16, v9
	v_and_b32_e32 v119, 0xffff0000, v9
	v_lshlrev_b32_e32 v120, 16, v10
	v_and_b32_e32 v121, 0xffff0000, v10
	v_lshlrev_b32_e32 v122, 16, v11
	v_and_b32_e32 v123, 0xffff0000, v11
	v_pk_add_f32 v[100:101], v[100:101], v[116:117]
	v_pk_add_f32 v[102:103], v[102:103], v[118:119]
	v_pk_add_f32 v[104:105], v[104:105], v[120:121]
	v_pk_add_f32 v[106:107], v[106:107], v[122:123]
	v_fma_f32 v116, v154, v100, -v116
	v_fma_f32 v117, v154, v101, -v117
	v_fma_f32 v118, v154, v102, -v118
	v_fma_f32 v119, v154, v103, -v119
	v_fma_f32 v120, v154, v104, -v120
	v_fma_f32 v121, v154, v105, -v121
	v_fma_f32 v122, v154, v106, -v122
	v_fma_f32 v123, v154, v107, -v123
	v_mul_f32_e32 v116, v108, v116
	v_mul_f32_e32 v117, v109, v117
	v_mul_f32_e32 v118, v110, v118
	v_mul_f32_e32 v119, v111, v119
	v_mul_f32_e32 v120, v112, v120
	v_mul_f32_e32 v121, v113, v121
	v_mul_f32_e32 v122, v114, v122
	v_mul_f32_e32 v123, v115, v123
	v_lshlrev_b32_e32 v128, 16, v40
	v_and_b32_e32 v129, 0xffff0000, v40
	v_mul_f32_e32 v116, v116, v128
	v_mul_f32_e32 v117, v117, v129
	v_cvt_pk_bf16_f32 v124, v116, v117
	v_lshlrev_b32_e32 v128, 16, v41
	v_and_b32_e32 v129, 0xffff0000, v41
	v_mul_f32_e32 v118, v118, v128
	v_mul_f32_e32 v119, v119, v129
	v_cvt_pk_bf16_f32 v125, v118, v119
	v_lshlrev_b32_e32 v128, 16, v42
	v_and_b32_e32 v129, 0xffff0000, v42
	v_mul_f32_e32 v120, v120, v128
	v_mul_f32_e32 v121, v121, v129
	v_cvt_pk_bf16_f32 v126, v120, v121
	v_lshlrev_b32_e32 v128, 16, v43
	v_and_b32_e32 v129, 0xffff0000, v43
	v_mul_f32_e32 v122, v122, v128
	v_mul_f32_e32 v123, v123, v129
	v_cvt_pk_bf16_f32 v127, v122, v123
	s_add_u32 s98, s12, 0x1000
	s_addc_u32 s99, s13, 0
	global_store_dwordx4 v2, v[124:127], s[98:99]
	v_lshlrev_b32_e32 v116, 16, v72
	v_and_b32_e32 v117, 0xffff0000, v72
	v_lshlrev_b32_e32 v118, 16, v73
	v_and_b32_e32 v119, 0xffff0000, v73
	v_lshlrev_b32_e32 v120, 16, v74
	v_and_b32_e32 v121, 0xffff0000, v74
	v_lshlrev_b32_e32 v122, 16, v75
	v_and_b32_e32 v123, 0xffff0000, v75
	v_pk_add_f32 v[100:101], v[100:101], v[116:117] neg_lo:[0,1] neg_hi:[0,1]
	v_pk_add_f32 v[102:103], v[102:103], v[118:119] neg_lo:[0,1] neg_hi:[0,1]
	v_pk_add_f32 v[104:105], v[104:105], v[120:121] neg_lo:[0,1] neg_hi:[0,1]
	v_pk_add_f32 v[106:107], v[106:107], v[122:123] neg_lo:[0,1] neg_hi:[0,1]
	s_add_u32 s98, s8, 0x9000
	s_addc_u32 s99, s9, 0
	global_load_dwordx4 v[8:11], v2, s[98:99]
	s_add_u32 s98, s10, 0x9000
	s_addc_u32 s99, s11, 0
	global_load_dwordx4 v[40:43], v2, s[98:99] nt
	s_add_u32 s98, s40, 0x9000
	s_addc_u32 s99, s41, 0
	global_load_dwordx4 v[72:75], v2, s[98:99]
	s_add_u32 s100, s100, 1
	s_waitcnt vmcnt(28)
	v_mov_b32_e32 v154, s38
	s_cmp_lt_u32 s100, s30
	s_cbranch_scc0 .Lpool_fa_2
	v_mov_b32_e32 v76, 0
	v_mov_b32_e32 v77, 0
	v_mov_b32_e32 v78, 0
	v_mov_b32_e32 v79, 0
	s_add_u32 s98, s100, 1
	v_cvt_f32_u32_e32 v116, s98
	v_div_scale_f32 v117, s[98:99], v116, v116, 1.0
	v_rcp_f32_e32 v118, v117
	s_nop 1
	v_fma_f32 v119, -v117, v118, 1.0
	v_fmac_f32_e32 v118, v119, v118
	v_div_scale_f32 v119, vcc, 1.0, v116, 1.0
	v_mul_f32_e32 v120, v119, v118
	v_fma_f32 v121, -v117, v120, v119
	v_fmac_f32_e32 v120, v121, v118
	v_fma_f32 v117, -v117, v120, v119
	s_nop 1
	v_div_fmas_f32 v117, v117, v118, v120
	v_div_fixup_f32 v154, v117, v116, 1.0
.Lpool_fa_2:
	v_lshlrev_b32_e32 v116, 16, v12
	v_and_b32_e32 v117, 0xffff0000, v12
	v_lshlrev_b32_e32 v118, 16, v13
	v_and_b32_e32 v119, 0xffff0000, v13
	v_lshlrev_b32_e32 v120, 16, v14
	v_and_b32_e32 v121, 0xffff0000, v14
	v_lshlrev_b32_e32 v122, 16, v15
	v_and_b32_e32 v123, 0xffff0000, v15
	v_pk_add_f32 v[100:101], v[100:101], v[116:117]
	v_pk_add_f32 v[102:103], v[102:103], v[118:119]
	v_pk_add_f32 v[104:105], v[104:105], v[120:121]
	v_pk_add_f32 v[106:107], v[106:107], v[122:123]
	v_fma_f32 v116, v154, v100, -v116
	v_fma_f32 v117, v154, v101, -v117
	v_fma_f32 v118, v154, v102, -v118
	v_fma_f32 v119, v154, v103, -v119
	v_fma_f32 v120, v154, v104, -v120
	v_fma_f32 v121, v154, v105, -v121
	v_fma_f32 v122, v154, v106, -v122
	v_fma_f32 v123, v154, v107, -v123
	v_mul_f32_e32 v116, v108, v116
	v_mul_f32_e32 v117, v109, v117
	v_mul_f32_e32 v118, v110, v118
	v_mul_f32_e32 v119, v111, v119
	v_mul_f32_e32 v120, v112, v120
	v_mul_f32_e32 v121, v113, v121
	v_mul_f32_e32 v122, v114, v122
	v_mul_f32_e32 v123, v115, v123
	v_lshlrev_b32_e32 v128, 16, v44
	v_and_b32_e32 v129, 0xffff0000, v44
	v_mul_f32_e32 v116, v116, v128
	v_mul_f32_e32 v117, v117, v129
	v_cvt_pk_bf16_f32 v124, v116, v117
	v_lshlrev_b32_e32 v128, 16, v45
	v_and_b32_e32 v129, 0xffff0000, v45
	v_mul_f32_e32 v118, v118, v128
	v_mul_f32_e32 v119, v119, v129
	v_cvt_pk_bf16_f32 v125, v118, v119
	v_lshlrev_b32_e32 v128, 16, v46
	v_and_b32_e32 v129, 0xffff0000, v46
	v_mul_f32_e32 v120, v120, v128
	v_mul_f32_e32 v121, v121, v129
	v_cvt_pk_bf16_f32 v126, v120, v121
	v_lshlrev_b32_e32 v128, 16, v47
	v_and_b32_e32 v129, 0xffff0000, v47
	v_mul_f32_e32 v122, v122, v128
	v_mul_f32_e32 v123, v123, v129
	v_cvt_pk_bf16_f32 v127, v122, v123
	s_add_u32 s98, s12, 0x2000
	s_addc_u32 s99, s13, 0
	global_store_dwordx4 v2, v[124:127], s[98:99]
	v_lshlrev_b32_e32 v116, 16, v76
	v_and_b32_e32 v117, 0xffff0000, v76
	v_lshlrev_b32_e32 v118, 16, v77
	v_and_b32_e32 v119, 0xffff0000, v77
	v_lshlrev_b32_e32 v120, 16, v78
	v_and_b32_e32 v121, 0xffff0000, v78
	v_lshlrev_b32_e32 v122, 16, v79
	v_and_b32_e32 v123, 0xffff0000, v79
	v_pk_add_f32 v[100:101], v[100:101], v[116:117] neg_lo:[0,1] neg_hi:[0,1]
	v_pk_add_f32 v[102:103], v[102:103], v[118:119] neg_lo:[0,1] neg_hi:[0,1]
	v_pk_add_f32 v[104:105], v[104:105], v[120:121] neg_lo:[0,1] neg_hi:[0,1]
	v_pk_add_f32 v[106:107], v[106:107], v[122:123] neg_lo:[0,1] neg_hi:[0,1]
	s_add_u32 s98, s8, 0xa000
	s_addc_u32 s99, s9, 0
	global_load_dwordx4 v[12:15], v2, s[98:99]
	s_add_u32 s98, s10, 0xa000
	s_addc_u32 s99, s11, 0
	global_load_dwordx4 v[44:47], v2, s[98:99] nt
	s_add_u32 s98, s40, 0xa000
	s_addc_u32 s99, s41, 0
	global_load_dwordx4 v[76:79], v2, s[98:99]
	s_add_u32 s100, s100, 1
	s_waitcnt vmcnt(28)
	v_mov_b32_e32 v154, s38
	s_cmp_lt_u32 s100, s30
	s_cbranch_scc0 .Lpool_fa_3
	v_mov_b32_e32 v80, 0
	v_mov_b32_e32 v81, 0
	v_mov_b32_e32 v82, 0
	v_mov_b32_e32 v83, 0
	s_add_u32 s98, s100, 1
	v_cvt_f32_u32_e32 v116, s98
	v_div_scale_f32 v117, s[98:99], v116, v116, 1.0
	v_rcp_f32_e32 v118, v117
	s_nop 1
	v_fma_f32 v119, -v117, v118, 1.0
	v_fmac_f32_e32 v118, v119, v118
	v_div_scale_f32 v119, vcc, 1.0, v116, 1.0
	v_mul_f32_e32 v120, v119, v118
	v_fma_f32 v121, -v117, v120, v119
	v_fmac_f32_e32 v120, v121, v118
	v_fma_f32 v117, -v117, v120, v119
	s_nop 1
	v_div_fmas_f32 v117, v117, v118, v120
	v_div_fixup_f32 v154, v117, v116, 1.0
.Lpool_fa_3:
	v_lshlrev_b32_e32 v116, 16, v16
	v_and_b32_e32 v117, 0xffff0000, v16
	v_lshlrev_b32_e32 v118, 16, v17
	v_and_b32_e32 v119, 0xffff0000, v17
	v_lshlrev_b32_e32 v120, 16, v18
	v_and_b32_e32 v121, 0xffff0000, v18
	v_lshlrev_b32_e32 v122, 16, v19
	v_and_b32_e32 v123, 0xffff0000, v19
	v_pk_add_f32 v[100:101], v[100:101], v[116:117]
	v_pk_add_f32 v[102:103], v[102:103], v[118:119]
	v_pk_add_f32 v[104:105], v[104:105], v[120:121]
	v_pk_add_f32 v[106:107], v[106:107], v[122:123]
	v_fma_f32 v116, v154, v100, -v116
	v_fma_f32 v117, v154, v101, -v117
	v_fma_f32 v118, v154, v102, -v118
	v_fma_f32 v119, v154, v103, -v119
	v_fma_f32 v120, v154, v104, -v120
	v_fma_f32 v121, v154, v105, -v121
	v_fma_f32 v122, v154, v106, -v122
	v_fma_f32 v123, v154, v107, -v123
	v_mul_f32_e32 v116, v108, v116
	v_mul_f32_e32 v117, v109, v117
	v_mul_f32_e32 v118, v110, v118
	v_mul_f32_e32 v119, v111, v119
	v_mul_f32_e32 v120, v112, v120
	v_mul_f32_e32 v121, v113, v121
	v_mul_f32_e32 v122, v114, v122
	v_mul_f32_e32 v123, v115, v123
	v_lshlrev_b32_e32 v128, 16, v48
	v_and_b32_e32 v129, 0xffff0000, v48
	v_mul_f32_e32 v116, v116, v128
	v_mul_f32_e32 v117, v117, v129
	v_cvt_pk_bf16_f32 v124, v116, v117
	v_lshlrev_b32_e32 v128, 16, v49
	v_and_b32_e32 v129, 0xffff0000, v49
	v_mul_f32_e32 v118, v118, v128
	v_mul_f32_e32 v119, v119, v129
	v_cvt_pk_bf16_f32 v125, v118, v119
	v_lshlrev_b32_e32 v128, 16, v50
	v_and_b32_e32 v129, 0xffff0000, v50
	v_mul_f32_e32 v120, v120, v128
	v_mul_f32_e32 v121, v121, v129
	v_cvt_pk_bf16_f32 v126, v120, v121
	v_lshlrev_b32_e32 v128, 16, v51
	v_and_b32_e32 v129, 0xffff0000, v51
	v_mul_f32_e32 v122, v122, v128
	v_mul_f32_e32 v123, v123, v129
	v_cvt_pk_bf16_f32 v127, v122, v123
	s_add_u32 s98, s12, 0x3000
	s_addc_u32 s99, s13, 0
	global_store_dwordx4 v2, v[124:127], s[98:99]
	v_lshlrev_b32_e32 v116, 16, v80
	v_and_b32_e32 v117, 0xffff0000, v80
	v_lshlrev_b32_e32 v118, 16, v81
	v_and_b32_e32 v119, 0xffff0000, v81
	v_lshlrev_b32_e32 v120, 16, v82
	v_and_b32_e32 v121, 0xffff0000, v82
	v_lshlrev_b32_e32 v122, 16, v83
	v_and_b32_e32 v123, 0xffff0000, v83
	v_pk_add_f32 v[100:101], v[100:101], v[116:117] neg_lo:[0,1] neg_hi:[0,1]
	v_pk_add_f32 v[102:103], v[102:103], v[118:119] neg_lo:[0,1] neg_hi:[0,1]
	v_pk_add_f32 v[104:105], v[104:105], v[120:121] neg_lo:[0,1] neg_hi:[0,1]
	v_pk_add_f32 v[106:107], v[106:107], v[122:123] neg_lo:[0,1] neg_hi:[0,1]
	s_add_u32 s98, s8, 0xb000
	s_addc_u32 s99, s9, 0
	global_load_dwordx4 v[16:19], v2, s[98:99]
	s_add_u32 s98, s10, 0xb000
	s_addc_u32 s99, s11, 0
	global_load_dwordx4 v[48:51], v2, s[98:99] nt
	s_add_u32 s98, s40, 0xb000
	s_addc_u32 s99, s41, 0
	global_load_dwordx4 v[80:83], v2, s[98:99]
	s_add_u32 s100, s100, 1
	s_waitcnt vmcnt(28)
	v_mov_b32_e32 v154, s38
	s_cmp_lt_u32 s100, s30
	s_cbranch_scc0 .Lpool_fa_4
	v_mov_b32_e32 v84, 0
	v_mov_b32_e32 v85, 0
	v_mov_b32_e32 v86, 0
	v_mov_b32_e32 v87, 0
	s_add_u32 s98, s100, 1
	v_cvt_f32_u32_e32 v116, s98
	v_div_scale_f32 v117, s[98:99], v116, v116, 1.0
	v_rcp_f32_e32 v118, v117
	s_nop 1
	v_fma_f32 v119, -v117, v118, 1.0
	v_fmac_f32_e32 v118, v119, v118
	v_div_scale_f32 v119, vcc, 1.0, v116, 1.0
	v_mul_f32_e32 v120, v119, v118
	v_fma_f32 v121, -v117, v120, v119
	v_fmac_f32_e32 v120, v121, v118
	v_fma_f32 v117, -v117, v120, v119
	s_nop 1
	v_div_fmas_f32 v117, v117, v118, v120
	v_div_fixup_f32 v154, v117, v116, 1.0
.Lpool_fa_4:
	v_lshlrev_b32_e32 v116, 16, v20
	v_and_b32_e32 v117, 0xffff0000, v20
	v_lshlrev_b32_e32 v118, 16, v21
	v_and_b32_e32 v119, 0xffff0000, v21
	v_lshlrev_b32_e32 v120, 16, v22
	v_and_b32_e32 v121, 0xffff0000, v22
	v_lshlrev_b32_e32 v122, 16, v23
	v_and_b32_e32 v123, 0xffff0000, v23
	v_pk_add_f32 v[100:101], v[100:101], v[116:117]
	v_pk_add_f32 v[102:103], v[102:103], v[118:119]
	v_pk_add_f32 v[104:105], v[104:105], v[120:121]
	v_pk_add_f32 v[106:107], v[106:107], v[122:123]
	v_fma_f32 v116, v154, v100, -v116
	v_fma_f32 v117, v154, v101, -v117
	v_fma_f32 v118, v154, v102, -v118
	v_fma_f32 v119, v154, v103, -v119
	v_fma_f32 v120, v154, v104, -v120
	v_fma_f32 v121, v154, v105, -v121
	v_fma_f32 v122, v154, v106, -v122
	v_fma_f32 v123, v154, v107, -v123
	v_mul_f32_e32 v116, v108, v116
	v_mul_f32_e32 v117, v109, v117
	v_mul_f32_e32 v118, v110, v118
	v_mul_f32_e32 v119, v111, v119
	v_mul_f32_e32 v120, v112, v120
	v_mul_f32_e32 v121, v113, v121
	v_mul_f32_e32 v122, v114, v122
	v_mul_f32_e32 v123, v115, v123
	v_lshlrev_b32_e32 v128, 16, v52
	v_and_b32_e32 v129, 0xffff0000, v52
	v_mul_f32_e32 v116, v116, v128
	v_mul_f32_e32 v117, v117, v129
	v_cvt_pk_bf16_f32 v124, v116, v117
	v_lshlrev_b32_e32 v128, 16, v53
	v_and_b32_e32 v129, 0xffff0000, v53
	v_mul_f32_e32 v118, v118, v128
	v_mul_f32_e32 v119, v119, v129
	v_cvt_pk_bf16_f32 v125, v118, v119
	v_lshlrev_b32_e32 v128, 16, v54
	v_and_b32_e32 v129, 0xffff0000, v54
	v_mul_f32_e32 v120, v120, v128
	v_mul_f32_e32 v121, v121, v129
	v_cvt_pk_bf16_f32 v126, v120, v121
	v_lshlrev_b32_e32 v128, 16, v55
	v_and_b32_e32 v129, 0xffff0000, v55
	v_mul_f32_e32 v122, v122, v128
	v_mul_f32_e32 v123, v123, v129
	v_cvt_pk_bf16_f32 v127, v122, v123
	s_add_u32 s98, s12, 0x4000
	s_addc_u32 s99, s13, 0
	global_store_dwordx4 v2, v[124:127], s[98:99]
	v_lshlrev_b32_e32 v116, 16, v84
	v_and_b32_e32 v117, 0xffff0000, v84
	v_lshlrev_b32_e32 v118, 16, v85
	v_and_b32_e32 v119, 0xffff0000, v85
	v_lshlrev_b32_e32 v120, 16, v86
	v_and_b32_e32 v121, 0xffff0000, v86
	v_lshlrev_b32_e32 v122, 16, v87
	v_and_b32_e32 v123, 0xffff0000, v87
	v_pk_add_f32 v[100:101], v[100:101], v[116:117] neg_lo:[0,1] neg_hi:[0,1]
	v_pk_add_f32 v[102:103], v[102:103], v[118:119] neg_lo:[0,1] neg_hi:[0,1]
	v_pk_add_f32 v[104:105], v[104:105], v[120:121] neg_lo:[0,1] neg_hi:[0,1]
	v_pk_add_f32 v[106:107], v[106:107], v[122:123] neg_lo:[0,1] neg_hi:[0,1]
	s_add_u32 s98, s8, 0xc000
	s_addc_u32 s99, s9, 0
	global_load_dwordx4 v[20:23], v2, s[98:99]
	s_add_u32 s98, s10, 0xc000
	s_addc_u32 s99, s11, 0
	global_load_dwordx4 v[52:55], v2, s[98:99] nt
	s_add_u32 s98, s40, 0xc000
	s_addc_u32 s99, s41, 0
	global_load_dwordx4 v[84:87], v2, s[98:99]
	s_add_u32 s100, s100, 1
	s_waitcnt vmcnt(28)
	v_mov_b32_e32 v154, s38
	s_cmp_lt_u32 s100, s30
	s_cbranch_scc0 .Lpool_fa_5
	v_mov_b32_e32 v88, 0
	v_mov_b32_e32 v89, 0
	v_mov_b32_e32 v90, 0
	v_mov_b32_e32 v91, 0
	s_add_u32 s98, s100, 1
	v_cvt_f32_u32_e32 v116, s98
	v_div_scale_f32 v117, s[98:99], v116, v116, 1.0
	v_rcp_f32_e32 v118, v117
	s_nop 1
	v_fma_f32 v119, -v117, v118, 1.0
	v_fmac_f32_e32 v118, v119, v118
	v_div_scale_f32 v119, vcc, 1.0, v116, 1.0
	v_mul_f32_e32 v120, v119, v118
	v_fma_f32 v121, -v117, v120, v119
	v_fmac_f32_e32 v120, v121, v118
	v_fma_f32 v117, -v117, v120, v119
	s_nop 1
	v_div_fmas_f32 v117, v117, v118, v120
	v_div_fixup_f32 v154, v117, v116, 1.0
.Lpool_fa_5:
	v_lshlrev_b32_e32 v116, 16, v24
	v_and_b32_e32 v117, 0xffff0000, v24
	v_lshlrev_b32_e32 v118, 16, v25
	v_and_b32_e32 v119, 0xffff0000, v25
	v_lshlrev_b32_e32 v120, 16, v26
	v_and_b32_e32 v121, 0xffff0000, v26
	v_lshlrev_b32_e32 v122, 16, v27
	v_and_b32_e32 v123, 0xffff0000, v27
	v_pk_add_f32 v[100:101], v[100:101], v[116:117]
	v_pk_add_f32 v[102:103], v[102:103], v[118:119]
	v_pk_add_f32 v[104:105], v[104:105], v[120:121]
	v_pk_add_f32 v[106:107], v[106:107], v[122:123]
	v_fma_f32 v116, v154, v100, -v116
	v_fma_f32 v117, v154, v101, -v117
	v_fma_f32 v118, v154, v102, -v118
	v_fma_f32 v119, v154, v103, -v119
	v_fma_f32 v120, v154, v104, -v120
	v_fma_f32 v121, v154, v105, -v121
	v_fma_f32 v122, v154, v106, -v122
	v_fma_f32 v123, v154, v107, -v123
	v_mul_f32_e32 v116, v108, v116
	v_mul_f32_e32 v117, v109, v117
	v_mul_f32_e32 v118, v110, v118
	v_mul_f32_e32 v119, v111, v119
	v_mul_f32_e32 v120, v112, v120
	v_mul_f32_e32 v121, v113, v121
	v_mul_f32_e32 v122, v114, v122
	v_mul_f32_e32 v123, v115, v123
	v_lshlrev_b32_e32 v128, 16, v56
	v_and_b32_e32 v129, 0xffff0000, v56
	v_mul_f32_e32 v116, v116, v128
	v_mul_f32_e32 v117, v117, v129
	v_cvt_pk_bf16_f32 v124, v116, v117
	v_lshlrev_b32_e32 v128, 16, v57
	v_and_b32_e32 v129, 0xffff0000, v57
	v_mul_f32_e32 v118, v118, v128
	v_mul_f32_e32 v119, v119, v129
	v_cvt_pk_bf16_f32 v125, v118, v119
	v_lshlrev_b32_e32 v128, 16, v58
	v_and_b32_e32 v129, 0xffff0000, v58
	v_mul_f32_e32 v120, v120, v128
	v_mul_f32_e32 v121, v121, v129
	v_cvt_pk_bf16_f32 v126, v120, v121
	v_lshlrev_b32_e32 v128, 16, v59
	v_and_b32_e32 v129, 0xffff0000, v59
	v_mul_f32_e32 v122, v122, v128
	v_mul_f32_e32 v123, v123, v129
	v_cvt_pk_bf16_f32 v127, v122, v123
	s_add_u32 s98, s12, 0x5000
	s_addc_u32 s99, s13, 0
	global_store_dwordx4 v2, v[124:127], s[98:99]
	v_lshlrev_b32_e32 v116, 16, v88
	v_and_b32_e32 v117, 0xffff0000, v88
	v_lshlrev_b32_e32 v118, 16, v89
	v_and_b32_e32 v119, 0xffff0000, v89
	v_lshlrev_b32_e32 v120, 16, v90
	v_and_b32_e32 v121, 0xffff0000, v90
	v_lshlrev_b32_e32 v122, 16, v91
	v_and_b32_e32 v123, 0xffff0000, v91
	v_pk_add_f32 v[100:101], v[100:101], v[116:117] neg_lo:[0,1] neg_hi:[0,1]
	v_pk_add_f32 v[102:103], v[102:103], v[118:119] neg_lo:[0,1] neg_hi:[0,1]
	v_pk_add_f32 v[104:105], v[104:105], v[120:121] neg_lo:[0,1] neg_hi:[0,1]
	v_pk_add_f32 v[106:107], v[106:107], v[122:123] neg_lo:[0,1] neg_hi:[0,1]
	s_add_u32 s98, s8, 0xd000
	s_addc_u32 s99, s9, 0
	global_load_dwordx4 v[24:27], v2, s[98:99]
	s_add_u32 s98, s10, 0xd000
	s_addc_u32 s99, s11, 0
	global_load_dwordx4 v[56:59], v2, s[98:99] nt
	s_add_u32 s98, s40, 0xd000
	s_addc_u32 s99, s41, 0
	global_load_dwordx4 v[88:91], v2, s[98:99]
	s_add_u32 s100, s100, 1
	s_waitcnt vmcnt(28)
	v_mov_b32_e32 v154, s38
	s_cmp_lt_u32 s100, s30
	s_cbranch_scc0 .Lpool_fa_6
	v_mov_b32_e32 v92, 0
	v_mov_b32_e32 v93, 0
	v_mov_b32_e32 v94, 0
	v_mov_b32_e32 v95, 0
	s_add_u32 s98, s100, 1
	v_cvt_f32_u32_e32 v116, s98
	v_div_scale_f32 v117, s[98:99], v116, v116, 1.0
	v_rcp_f32_e32 v118, v117
	s_nop 1
	v_fma_f32 v119, -v117, v118, 1.0
	v_fmac_f32_e32 v118, v119, v118
	v_div_scale_f32 v119, vcc, 1.0, v116, 1.0
	v_mul_f32_e32 v120, v119, v118
	v_fma_f32 v121, -v117, v120, v119
	v_fmac_f32_e32 v120, v121, v118
	v_fma_f32 v117, -v117, v120, v119
	s_nop 1
	v_div_fmas_f32 v117, v117, v118, v120
	v_div_fixup_f32 v154, v117, v116, 1.0
.Lpool_fa_6:
	v_lshlrev_b32_e32 v116, 16, v28
	v_and_b32_e32 v117, 0xffff0000, v28
	v_lshlrev_b32_e32 v118, 16, v29
	v_and_b32_e32 v119, 0xffff0000, v29
	v_lshlrev_b32_e32 v120, 16, v30
	v_and_b32_e32 v121, 0xffff0000, v30
	v_lshlrev_b32_e32 v122, 16, v31
	v_and_b32_e32 v123, 0xffff0000, v31
	v_pk_add_f32 v[100:101], v[100:101], v[116:117]
	v_pk_add_f32 v[102:103], v[102:103], v[118:119]
	v_pk_add_f32 v[104:105], v[104:105], v[120:121]
	v_pk_add_f32 v[106:107], v[106:107], v[122:123]
	v_fma_f32 v116, v154, v100, -v116
	v_fma_f32 v117, v154, v101, -v117
	v_fma_f32 v118, v154, v102, -v118
	v_fma_f32 v119, v154, v103, -v119
	v_fma_f32 v120, v154, v104, -v120
	v_fma_f32 v121, v154, v105, -v121
	v_fma_f32 v122, v154, v106, -v122
	v_fma_f32 v123, v154, v107, -v123
	v_mul_f32_e32 v116, v108, v116
	v_mul_f32_e32 v117, v109, v117
	v_mul_f32_e32 v118, v110, v118
	v_mul_f32_e32 v119, v111, v119
	v_mul_f32_e32 v120, v112, v120
	v_mul_f32_e32 v121, v113, v121
	v_mul_f32_e32 v122, v114, v122
	v_mul_f32_e32 v123, v115, v123
	v_lshlrev_b32_e32 v128, 16, v60
	v_and_b32_e32 v129, 0xffff0000, v60
	v_mul_f32_e32 v116, v116, v128
	v_mul_f32_e32 v117, v117, v129
	v_cvt_pk_bf16_f32 v124, v116, v117
	v_lshlrev_b32_e32 v128, 16, v61
	v_and_b32_e32 v129, 0xffff0000, v61
	v_mul_f32_e32 v118, v118, v128
	v_mul_f32_e32 v119, v119, v129
	v_cvt_pk_bf16_f32 v125, v118, v119
	v_lshlrev_b32_e32 v128, 16, v62
	v_and_b32_e32 v129, 0xffff0000, v62
	v_mul_f32_e32 v120, v120, v128
	v_mul_f32_e32 v121, v121, v129
	v_cvt_pk_bf16_f32 v126, v120, v121
	v_lshlrev_b32_e32 v128, 16, v63
	v_and_b32_e32 v129, 0xffff0000, v63
	v_mul_f32_e32 v122, v122, v128
	v_mul_f32_e32 v123, v123, v129
	v_cvt_pk_bf16_f32 v127, v122, v123
	s_add_u32 s98, s12, 0x6000
	s_addc_u32 s99, s13, 0
	global_store_dwordx4 v2, v[124:127], s[98:99]
	v_lshlrev_b32_e32 v116, 16, v92
	v_and_b32_e32 v117, 0xffff0000, v92
	v_lshlrev_b32_e32 v118, 16, v93
	v_and_b32_e32 v119, 0xffff0000, v93
	v_lshlrev_b32_e32 v120, 16, v94
	v_and_b32_e32 v121, 0xffff0000, v94
	v_lshlrev_b32_e32 v122, 16, v95
	v_and_b32_e32 v123, 0xffff0000, v95
	v_pk_add_f32 v[100:101], v[100:101], v[116:117] neg_lo:[0,1] neg_hi:[0,1]
	v_pk_add_f32 v[102:103], v[102:103], v[118:119] neg_lo:[0,1] neg_hi:[0,1]
	v_pk_add_f32 v[104:105], v[104:105], v[120:121] neg_lo:[0,1] neg_hi:[0,1]
	v_pk_add_f32 v[106:107], v[106:107], v[122:123] neg_lo:[0,1] neg_hi:[0,1]
	s_add_u32 s98, s8, 0xe000
	s_addc_u32 s99, s9, 0
	global_load_dwordx4 v[28:31], v2, s[98:99]
	s_add_u32 s98, s10, 0xe000
	s_addc_u32 s99, s11, 0
	global_load_dwordx4 v[60:63], v2, s[98:99] nt
	s_add_u32 s98, s40, 0xe000
	s_addc_u32 s99, s41, 0
	global_load_dwordx4 v[92:95], v2, s[98:99]
	s_add_u32 s100, s100, 1
	s_waitcnt vmcnt(28)
	v_mov_b32_e32 v154, s38
	s_cmp_lt_u32 s100, s30
	s_cbranch_scc0 .Lpool_fa_7
	v_mov_b32_e32 v96, 0
	v_mov_b32_e32 v97, 0
	v_mov_b32_e32 v98, 0
	v_mov_b32_e32 v99, 0
	s_add_u32 s98, s100, 1
	v_cvt_f32_u32_e32 v116, s98
	v_div_scale_f32 v117, s[98:99], v116, v116, 1.0
	v_rcp_f32_e32 v118, v117
	s_nop 1
	v_fma_f32 v119, -v117, v118, 1.0
	v_fmac_f32_e32 v118, v119, v118
	v_div_scale_f32 v119, vcc, 1.0, v116, 1.0
	v_mul_f32_e32 v120, v119, v118
	v_fma_f32 v121, -v117, v120, v119
	v_fmac_f32_e32 v120, v121, v118
	v_fma_f32 v117, -v117, v120, v119
	s_nop 1
	v_div_fmas_f32 v117, v117, v118, v120
	v_div_fixup_f32 v154, v117, v116, 1.0
.Lpool_fa_7:
	v_lshlrev_b32_e32 v116, 16, v32
	v_and_b32_e32 v117, 0xffff0000, v32
	v_lshlrev_b32_e32 v118, 16, v33
	v_and_b32_e32 v119, 0xffff0000, v33
	v_lshlrev_b32_e32 v120, 16, v34
	v_and_b32_e32 v121, 0xffff0000, v34
	v_lshlrev_b32_e32 v122, 16, v35
	v_and_b32_e32 v123, 0xffff0000, v35
	v_pk_add_f32 v[100:101], v[100:101], v[116:117]
	v_pk_add_f32 v[102:103], v[102:103], v[118:119]
	v_pk_add_f32 v[104:105], v[104:105], v[120:121]
	v_pk_add_f32 v[106:107], v[106:107], v[122:123]
	v_fma_f32 v116, v154, v100, -v116
	v_fma_f32 v117, v154, v101, -v117
	v_fma_f32 v118, v154, v102, -v118
	v_fma_f32 v119, v154, v103, -v119
	v_fma_f32 v120, v154, v104, -v120
	v_fma_f32 v121, v154, v105, -v121
	v_fma_f32 v122, v154, v106, -v122
	v_fma_f32 v123, v154, v107, -v123
	v_mul_f32_e32 v116, v108, v116
	v_mul_f32_e32 v117, v109, v117
	v_mul_f32_e32 v118, v110, v118
	v_mul_f32_e32 v119, v111, v119
	v_mul_f32_e32 v120, v112, v120
	v_mul_f32_e32 v121, v113, v121
	v_mul_f32_e32 v122, v114, v122
	v_mul_f32_e32 v123, v115, v123
	v_lshlrev_b32_e32 v128, 16, v64
	v_and_b32_e32 v129, 0xffff0000, v64
	v_mul_f32_e32 v116, v116, v128
	v_mul_f32_e32 v117, v117, v129
	v_cvt_pk_bf16_f32 v124, v116, v117
	v_lshlrev_b32_e32 v128, 16, v65
	v_and_b32_e32 v129, 0xffff0000, v65
	v_mul_f32_e32 v118, v118, v128
	v_mul_f32_e32 v119, v119, v129
	v_cvt_pk_bf16_f32 v125, v118, v119
	v_lshlrev_b32_e32 v128, 16, v66
	v_and_b32_e32 v129, 0xffff0000, v66
	v_mul_f32_e32 v120, v120, v128
	v_mul_f32_e32 v121, v121, v129
	v_cvt_pk_bf16_f32 v126, v120, v121
	v_lshlrev_b32_e32 v128, 16, v67
	v_and_b32_e32 v129, 0xffff0000, v67
	v_mul_f32_e32 v122, v122, v128
	v_mul_f32_e32 v123, v123, v129
	v_cvt_pk_bf16_f32 v127, v122, v123
	s_add_u32 s98, s12, 0x7000
	s_addc_u32 s99, s13, 0
	global_store_dwordx4 v2, v[124:127], s[98:99]
	v_lshlrev_b32_e32 v116, 16, v96
	v_and_b32_e32 v117, 0xffff0000, v96
	v_lshlrev_b32_e32 v118, 16, v97
	v_and_b32_e32 v119, 0xffff0000, v97
	v_lshlrev_b32_e32 v120, 16, v98
	v_and_b32_e32 v121, 0xffff0000, v98
	v_lshlrev_b32_e32 v122, 16, v99
	v_and_b32_e32 v123, 0xffff0000, v99
	v_pk_add_f32 v[100:101], v[100:101], v[116:117] neg_lo:[0,1] neg_hi:[0,1]
	v_pk_add_f32 v[102:103], v[102:103], v[118:119] neg_lo:[0,1] neg_hi:[0,1]
	v_pk_add_f32 v[104:105], v[104:105], v[120:121] neg_lo:[0,1] neg_hi:[0,1]
	v_pk_add_f32 v[106:107], v[106:107], v[122:123] neg_lo:[0,1] neg_hi:[0,1]
	s_add_u32 s98, s8, 0xf000
	s_addc_u32 s99, s9, 0
	global_load_dwordx4 v[32:35], v2, s[98:99]
	s_add_u32 s98, s10, 0xf000
	s_addc_u32 s99, s11, 0
	global_load_dwordx4 v[64:67], v2, s[98:99] nt
	s_add_u32 s98, s40, 0xf000
	s_addc_u32 s99, s41, 0
	global_load_dwordx4 v[96:99], v2, s[98:99]
	s_add_u32 s100, s100, 1
	s_add_u32 s8, s8, 0x8000
	s_addc_u32 s9, s9, 0
	s_add_u32 s10, s10, 0x8000
	s_addc_u32 s11, s11, 0
	s_add_u32 s12, s12, 0x8000
	s_addc_u32 s13, s13, 0
	s_add_u32 s40, s40, 0x8000
	s_addc_u32 s41, s41, 0
	s_sub_u32 s39, s39, 1
	s_cmp_lg_u32 s39, 0
	s_cbranch_scc1 .Lpool_batch
	s_waitcnt vmcnt(28)
	v_mov_b32_e32 v154, s38
	s_cmp_lt_u32 s100, s30
	s_cbranch_scc0 .Lpool_fb_0
	v_mov_b32_e32 v68, 0
	v_mov_b32_e32 v69, 0
	v_mov_b32_e32 v70, 0
	v_mov_b32_e32 v71, 0
	s_add_u32 s98, s100, 1
	v_cvt_f32_u32_e32 v116, s98
	v_div_scale_f32 v117, s[98:99], v116, v116, 1.0
	v_rcp_f32_e32 v118, v117
	s_nop 1
	v_fma_f32 v119, -v117, v118, 1.0
	v_fmac_f32_e32 v118, v119, v118
	v_div_scale_f32 v119, vcc, 1.0, v116, 1.0
	v_mul_f32_e32 v120, v119, v118
	v_fma_f32 v121, -v117, v120, v119
	v_fmac_f32_e32 v120, v121, v118
	v_fma_f32 v117, -v117, v120, v119
	s_nop 1
	v_div_fmas_f32 v117, v117, v118, v120
	v_div_fixup_f32 v154, v117, v116, 1.0
